# S11 plus SGU LDS bank-conflict fix: transposed T image column groups XOR-swizzled by row block (16-way ds_write_b16 conflict to 2-way), readers use 16 precomputed addresses
# baseline (speedup 1.0000x reference)
; __device__ __forceinline__ void phase_sgu(const Params& p, int l, LAS unsigned char* lds, const bf16_t* proj, const float* sgst, const bf16_t* sgw, bf16_t* ymix, int G, int wv) {
;     MK_TID(wv); const int lane = tid & 63, wave = wv, hi = lane >> 5, l32 = lane & 31;
;     const float* ng = p.sgu_norm_g + l * 512; const float* nb_ = p.sgu_norm_b + l * 512; const float* bs = p.sgu_b + l * 512;
;     for (int it = blockIdx.x; it < 1024; it += G) {
;         const int bc = it >> 2, head = it & 3, tok0 = bc * 128;
; #pragma unroll
;         for (int i = 0; i < 4; ++i) { const int c = tid + 512 * i, s = c >> 4, dc = c & 15; const size_t tok = tok0 + s;
;             const f32x4* sp = (const f32x4*)(sgst + tok * 16); const f32x4 q0 = sp[0], q1 = sp[1], q2 = sp[2], q3 = sp[3];
;             const float s1 = (q0[0] + q0[2]) + (q1[0] + q1[2]) + (q2[0] + q2[2]) + (q3[0] + q3[2]), s2 = (q0[1] + q0[3]) + (q1[1] + q1[3]) + (q2[1] + q2[3]) + (q3[1] + q3[3]);
;             const float mean = s1 * (1.f / 512.f), var = s2 * (1.f / 512.f) - mean * mean, rstd = __builtin_amdgcn_rsqf(fmaxf(var, 0.f) + EPS);
;             const u32x4 x = *(const u32x4*)(proj + tok * NIN + PJ_V + head * 128 + dc * 8);
;             const float xv[8] = {bf_lo(x.x), bf_hi(x.x), bf_lo(x.y), bf_hi(x.y), bf_lo(x.z), bf_hi(x.z), bf_lo(x.w), bf_hi(x.w)};
;             const f32x4 g0 = *(const f32x4*)(ng + head * 128 + dc * 8), g1 = *(const f32x4*)(ng + head * 128 + dc * 8 + 4);
;             const f32x4 b0 = *(const f32x4*)(nb_ + head * 128 + dc * 8), b1 = *(const f32x4*)(nb_ + head * 128 + dc * 8 + 4);
; #pragma unroll
;             for (int j = 0; j < 8; ++j) { const float gj = j < 4 ? g0[j & 3] : g1[j & 3], bj = j < 4 ? b0[j & 3] : b1[j & 3];
;                 const float v = (xv[j] - mean) * rstd * gj + bj;
;                 *(LAS bf16_t*)(lds + (dc * 8 + j) * SG_ROW + s * 2) = (bf16_t)(cvt_pk_bf16(v, 0.f) & 0xffffu); } }
;         const int tb = wave & 3, dh = wave >> 2;
;         const bf16_t* wrow = sgw + ((size_t)((l * 4 + head) * 128) + tb * 32 + l32) * 128 + 8 * hi;
;         bf16x8 af[8];
; #pragma unroll
;         for (int ks = 0; ks < 8; ++ks) { af[ks] = (bf16x8){0, 0, 0, 0, 0, 0, 0, 0}; if (ks < 2 * tb + 2) af[ks] = *(const bf16x8*)(wrow + 16 * ks); }
;         __syncthreads();
;         f32x16 acc0 = {0, 0, 0, 0, 0, 0, 0, 0, 0, 0, 0, 0, 0, 0, 0, 0}, acc1 = acc0;
.LBB0_390:
	s_or_b64 exec, exec, s[6:7]
	s_cmpk_lt_i32 s2, 0x400
	s_cselect_b64 s[0:1], -1, 0
	v_writelane_b32 v254, s0, 14
	s_mov_b32 s37, 0
	s_waitcnt lgkmcnt(0)
	v_mov_b32_e32 v0, v223
	v_writelane_b32 v254, s1, 15
	s_nop 0
	v_readlane_b32 s6, v254, 8
	s_cmp_lg_u32 s6, 0
	s_cselect_b64 s[0:1], -1, 0
	s_cmp_gt_u32 s6, 1
	s_cselect_b64 s[38:39], -1, 0
	s_cmp_eq_u32 s6, 3
	v_cndmask_b32_e64 v1, 0, 1, s[0:1]
	s_cselect_b64 s[40:41], -1, 0
	s_cmpk_gt_i32 s2, 0x3ff
	v_cmp_ne_u32_e64 s[6:7], 1, v1
	s_barrier
	s_cbranch_scc1 .LBB0_418
	s_load_dwordx4 s[8:11], s[94:95], 0x58
	s_load_dwordx2 s[42:43], s[94:95], 0x70
	s_lshl_b32 s0, s85, 4
	v_lshlrev_b32_e32 v2, 3, v0
	s_and_b32 s14, s0, 0x3fffffc0
	v_bfe_u32 v3, v0, 5, 1
	v_and_b32_e32 v2, 0x78, v2
	v_mov_b32_e32 v61, 0
	s_lshl_b32 s0, s14, 2
	v_lshlrev_b32_e32 v60, 2, v2
	v_lshlrev_b32_e32 v4, 4, v3
	v_mov_b32_e32 v5, v61
	v_and_b32_e32 v1, 31, v0
	s_add_i32 s15, s0, 0
	s_waitcnt lgkmcnt(0)
	v_lshl_add_u64 v[62:63], s[8:9], 0, v[60:61]
	v_readlane_b32 s8, v254, 3
	v_lshl_add_u64 v[6:7], s[20:21], 0, v[4:5]
	s_mov_b64 s[0:1], 0x3a00000
	v_lshl_add_u64 v[66:67], v[6:7], 0, s[0:1]
	v_or_b32_e32 v5, s14, v1
	v_lshlrev_b32_e32 v166, 1, v5
	v_and_b32_e32 v166, 0xf0, v166
	s_movk_i32 s0, 0x110
	v_lshl_or_b32 v3, v3, 2, s8
	v_ashrrev_i32_e32 v91, 4, v0
	v_add_u32_e32 v9, 0x200, v0
	v_add_u32_e32 v10, 0x400, v0
	v_add_u32_e32 v0, 0x600, v0
	v_or_b32_e32 v90, s8, v1
	v_mul_lo_u32 v5, v5, s0
	v_ashrrev_i32_e32 v92, 4, v9
	v_ashrrev_i32_e32 v93, 4, v10
	v_ashrrev_i32_e32 v94, 4, v0
	s_movk_i32 s0, 0x210
	v_mul_u32_u24_e32 v3, 0x210, v3
	v_lshlrev_b32_e32 v1, 2, v1
	v_add_u32_e32 v5, 0, v5
	v_add_u32_e32 v6, 0, v60
	v_lshl_add_u32 v7, v91, 1, 0
	v_mul_u32_u24_e32 v8, 0x110, v2
	v_lshl_add_u32 v9, v92, 1, 0
	v_lshl_add_u32 v10, v93, 1, 0
	v_lshl_add_u32 v0, v94, 1, 0
	v_add3_u32 v95, s15, v3, v1
	v_mul_lo_u32 v1, v91, s0
	v_mul_lo_u32 v3, v92, s0
	v_mul_lo_u32 v11, v93, s0
	v_mul_lo_u32 v12, v94, s0
	v_lshlrev_b32_e32 v70, 1, v2
	v_lshl_add_u64 v[64:65], s[10:11], 0, v[60:61]
	s_lshl_b32 s0, s2, 7
	s_lshl_b32 s1, s31, 7
	s_lshl_b32 s27, s2, 5
	s_mov_b32 s58, 0x3b000000
	s_movk_i32 s59, 0x2400
	v_mov_b64_e32 v[68:69], s[22:23]
	v_mov_b32_e32 v72, v70
	v_mov_b32_e32 v73, v61
	s_movk_i32 s60, 0x1000
	v_xor_b32_e32 v7, v7, v70
	v_xor_b32_e32 v9, v9, v70
	v_xor_b32_e32 v10, v10, v70
	v_xor_b32_e32 v0, v0, v70
	v_add_u32_e32 v96, v7, v8
	v_add_u32_e32 v97, v9, v8
	v_add_u32_e32 v98, v10, v8
	v_add_u32_e32 v99, v0, v8
	s_movk_i32 s61, 0x2000
	v_add_u32_e32 v100, v6, v1
	v_add_u32_e32 v101, v6, v3
	v_add_u32_e32 v102, v6, v11
	v_add_u32_e32 v103, v6, v12
	v_add_u32_e32 v104, v5, v4
	v_xor_b32_e32 v167, v4, v166
	v_mov_b32_e32 v168, v167
	v_add_u32_e32 v150, v5, v168
	v_xor_b32_e32 v169, 64, v168
	v_add_u32_e32 v169, v5, v169
	v_add_u32_e32 v158, 0x2200, v169
	v_xor_b32_e32 v168, 0x20, v167
	v_add_u32_e32 v151, v5, v168
	v_xor_b32_e32 v169, 64, v168
	v_add_u32_e32 v169, v5, v169
	v_add_u32_e32 v159, 0x2200, v169
	v_xor_b32_e32 v168, 0x40, v167
	v_add_u32_e32 v152, v5, v168
	v_xor_b32_e32 v169, 64, v168
	v_add_u32_e32 v169, v5, v169
	v_add_u32_e32 v160, 0x2200, v169
	v_xor_b32_e32 v168, 0x60, v167
	v_add_u32_e32 v153, v5, v168
	v_xor_b32_e32 v169, 64, v168
	v_add_u32_e32 v169, v5, v169
	v_add_u32_e32 v161, 0x2200, v169
	v_xor_b32_e32 v168, 0x80, v167
	v_add_u32_e32 v154, v5, v168
	v_xor_b32_e32 v169, 64, v168
	v_add_u32_e32 v169, v5, v169
	v_add_u32_e32 v162, 0x2200, v169
	v_xor_b32_e32 v168, 0xa0, v167
	v_add_u32_e32 v155, v5, v168
	v_xor_b32_e32 v169, 64, v168
	v_add_u32_e32 v169, v5, v169
	v_add_u32_e32 v163, 0x2200, v169
	v_xor_b32_e32 v168, 0xc0, v167
	v_add_u32_e32 v156, v5, v168
	v_xor_b32_e32 v169, 64, v168
	v_add_u32_e32 v169, v5, v169
	v_add_u32_e32 v164, 0x2200, v169
	v_xor_b32_e32 v168, 0xe0, v167
	v_add_u32_e32 v157, v5, v168
	v_xor_b32_e32 v169, 64, v168
	v_add_u32_e32 v169, v5, v169
	v_add_u32_e32 v165, 0x2200, v169
	s_mov_b32 s62, s2
	s_branch .LBB0_393

; #define LAS __attribute__((address_space(3)))
; __device__ __forceinline__ void phase_sgu(const Params& p, int l, LAS unsigned char* lds, const bf16_t* proj, const float* sgst, const bf16_t* sgw, bf16_t* ymix, int G, int wv) {
;     ...
;         __syncthreads();
;         f32x16 acc0 = {0, 0, 0, 0, 0, 0, 0, 0, 0, 0, 0, 0, 0, 0, 0, 0}, acc1 = acc0;
;         const LAS unsigned char* tb0 = lds + (dh * 64 + l32) * SG_ROW + hi * 16;
; #pragma unroll
;         for (int ks = 0; ks < 8; ++ks) if (ks < 2 * tb + 2) {
;             const bf16x8 b0 = *(const LAS bf16x8*)(tb0 + ks * 32), b1 = *(const LAS bf16x8*)(tb0 + 32 * SG_ROW + ks * 32);
;             acc0 = __builtin_amdgcn_mfma_f32_32x32x16_bf16(af[ks], b0, acc0, 0, 0, 0);
;             acc1 = __builtin_amdgcn_mfma_f32_32x32x16_bf16(af[ks], b1, acc1, 0, 0, 0);
;         }
.LBB0_406:
	s_waitcnt lgkmcnt(0)
	s_barrier
	ds_read_b128 v[0:3], v150
	ds_read_b128 v[106:109], v151
	ds_read_b128 v[20:23], v158
	ds_read_b128 v[110:113], v159
	s_waitcnt vmcnt(1) lgkmcnt(3)
	v_mfma_f32_32x32x16_bf16 v[0:15], v[16:19], v[0:3], 0
	s_and_b64 vcc, exec, s[6:7]
	s_waitcnt lgkmcnt(1)
	v_mfma_f32_32x32x16_bf16 v[16:31], v[16:19], v[20:23], 0
	s_waitcnt vmcnt(0)
	v_mfma_f32_32x32x16_bf16 v[0:15], v[40:43], v[106:109], v[0:15]
	s_waitcnt lgkmcnt(0)
	v_mfma_f32_32x32x16_bf16 v[16:31], v[40:43], v[110:113], v[16:31]
	s_cbranch_vccnz .LBB0_408
	ds_read_b128 v[40:43], v152
	ds_read_b128 v[106:109], v160
	s_waitcnt lgkmcnt(1)
	v_mfma_f32_32x32x16_bf16 v[0:15], v[32:35], v[40:43], v[0:15]
	s_waitcnt lgkmcnt(0)
	v_mfma_f32_32x32x16_bf16 v[16:31], v[32:35], v[106:109], v[16:31]
.LBB0_408:
	s_and_b64 vcc, exec, s[6:7]
	s_cbranch_vccnz .LBB0_410
	ds_read_b128 v[32:35], v153
	ds_read_b128 v[40:43], v161
	s_waitcnt lgkmcnt(1)
	v_mfma_f32_32x32x16_bf16 v[0:15], v[36:39], v[32:35], v[0:15]
	s_waitcnt lgkmcnt(0)
	v_mfma_f32_32x32x16_bf16 v[16:31], v[36:39], v[40:43], v[16:31]

; #define LAS __attribute__((address_space(3)))
; __device__ __forceinline__ void phase_sgu(const Params& p, int l, LAS unsigned char* lds, const bf16_t* proj, const float* sgst, const bf16_t* sgw, bf16_t* ymix, int G, int wv) {
;     ...
; #pragma unroll
;         for (int ks = 0; ks < 8; ++ks) if (ks < 2 * tb + 2) {
;             const bf16x8 b0 = *(const LAS bf16x8*)(tb0 + ks * 32), b1 = *(const LAS bf16x8*)(tb0 + 32 * SG_ROW + ks * 32);
;             acc0 = __builtin_amdgcn_mfma_f32_32x32x16_bf16(af[ks], b0, acc0, 0, 0, 0);
;             acc1 = __builtin_amdgcn_mfma_f32_32x32x16_bf16(af[ks], b1, acc1, 0, 0, 0);
;         }
.LBB0_414:
	ds_read_b128 v[32:35], v154
	ds_read_b128 v[36:39], v162
	s_waitcnt lgkmcnt(1)
	v_mfma_f32_32x32x16_bf16 v[0:15], v[44:47], v[32:35], v[0:15]
	s_waitcnt lgkmcnt(0)
	v_mfma_f32_32x32x16_bf16 v[16:31], v[44:47], v[36:39], v[16:31]
	s_and_b64 vcc, exec, s[8:9]
	s_cbranch_vccnz .LBB0_412
.LBB0_415:
	ds_read_b128 v[32:35], v155
	ds_read_b128 v[36:39], v163
	s_waitcnt lgkmcnt(1)
	v_mfma_f32_32x32x16_bf16 v[0:15], v[48:51], v[32:35], v[0:15]
	s_waitcnt lgkmcnt(0)
	v_mfma_f32_32x32x16_bf16 v[16:31], v[48:51], v[36:39], v[16:31]
	s_and_b64 vcc, exec, s[10:11]
	s_cbranch_vccnz .LBB0_413
.LBB0_416:
	ds_read_b128 v[32:35], v156
	ds_read_b128 v[36:39], v164
	s_waitcnt lgkmcnt(1)
	v_mfma_f32_32x32x16_bf16 v[0:15], v[52:55], v[32:35], v[0:15]
	s_waitcnt lgkmcnt(0)
	v_mfma_f32_32x32x16_bf16 v[16:31], v[52:55], v[36:39], v[16:31]
	s_and_b64 vcc, exec, s[10:11]
	s_cbranch_vccnz .LBB0_392
.LBB0_417:
	ds_read_b128 v[32:35], v157
	ds_read_b128 v[36:39], v165
	s_waitcnt lgkmcnt(1)
	v_mfma_f32_32x32x16_bf16 v[0:15], v[56:59], v[32:35], v[0:15]
	s_waitcnt lgkmcnt(0)
	v_mfma_f32_32x32x16_bf16 v[16:31], v[56:59], v[36:39], v[16:31]
	s_branch .LBB0_392

; __device__ __forceinline__ void phase_sgu(const Params& p, int l, LAS unsigned char* lds, const bf16_t* proj, const float* sgst, const bf16_t* sgw, bf16_t* ymix, int G, int wv) {
;     MK_TID(wv); const int lane = tid & 63, wave = wv, hi = lane >> 5, l32 = lane & 31;
;     const float* ng = p.sgu_norm_g + l * 512; const float* nb_ = p.sgu_norm_b + l * 512; const float* bs = p.sgu_b + l * 512;
;     for (int it = blockIdx.x; it < 1024; it += G) {
;         const int bc = it >> 2, head = it & 3, tok0 = bc * 128;
; #pragma unroll
;         for (int i = 0; i < 4; ++i) { const int c = tid + 512 * i, s = c >> 4, dc = c & 15; const size_t tok = tok0 + s;
;             const f32x4* sp = (const f32x4*)(sgst + tok * 16); const f32x4 q0 = sp[0], q1 = sp[1], q2 = sp[2], q3 = sp[3];
;             const float s1 = (q0[0] + q0[2]) + (q1[0] + q1[2]) + (q2[0] + q2[2]) + (q3[0] + q3[2]), s2 = (q0[1] + q0[3]) + (q1[1] + q1[3]) + (q2[1] + q2[3]) + (q3[1] + q3[3]);
;             const float mean = s1 * (1.f / 512.f), var = s2 * (1.f / 512.f) - mean * mean, rstd = __builtin_amdgcn_rsqf(fmaxf(var, 0.f) + EPS);
;             const u32x4 x = *(const u32x4*)(proj + tok * NIN + PJ_V + head * 128 + dc * 8);
;             const float xv[8] = {bf_lo(x.x), bf_hi(x.x), bf_lo(x.y), bf_hi(x.y), bf_lo(x.z), bf_hi(x.z), bf_lo(x.w), bf_hi(x.w)};
;             const f32x4 g0 = *(const f32x4*)(ng + head * 128 + dc * 8), g1 = *(const f32x4*)(ng + head * 128 + dc * 8 + 4);
;             const f32x4 b0 = *(const f32x4*)(nb_ + head * 128 + dc * 8), b1 = *(const f32x4*)(nb_ + head * 128 + dc * 8 + 4);
; #pragma unroll
;             for (int j = 0; j < 8; ++j) { const float gj = j < 4 ? g0[j & 3] : g1[j & 3], bj = j < 4 ? b0[j & 3] : b1[j & 3];
;                 const float v = (xv[j] - mean) * rstd * gj + bj;
;                 *(LAS bf16_t*)(lds + (dc * 8 + j) * SG_ROW + s * 2) = (bf16_t)(cvt_pk_bf16(v, 0.f) & 0xffffu); } }
;         const int tb = wave & 3, dh = wave >> 2;
;         const bf16_t* wrow = sgw + ((size_t)((l * 4 + head) * 128) + tb * 32 + l32) * 128 + 8 * hi;
;         bf16x8 af[8];
; #pragma unroll
;         for (int ks = 0; ks < 8; ++ks) { af[ks] = (bf16x8){0, 0, 0, 0, 0, 0, 0, 0}; if (ks < 2 * tb + 2) af[ks] = *(const bf16x8*)(wrow + 16 * ks); }
;         __syncthreads();
;         f32x16 acc0 = {0, 0, 0, 0, 0, 0, 0, 0, 0, 0, 0, 0, 0, 0, 0, 0}, acc1 = acc0;
.LBB0_955:
	s_or_b64 exec, exec, s[14:15]
	s_waitcnt lgkmcnt(0)
	v_mov_b32_e32 v0, v223
	s_and_b64 vcc, exec, s[12:13]
	s_barrier
	s_cbranch_vccnz .LBB0_983
	v_and_b32_e32 v1, 31, v0
	s_lshl_b32 s8, s85, 4
	v_readlane_b32 s14, v254, 3
	s_and_b32 s10, s8, 0x3fffffc0
	v_bfe_u32 v3, v0, 5, 1
	v_mov_b32_e32 v61, 0
	v_or_b32_e32 v4, s14, v1
	s_lshl_b32 s8, s10, 2
	v_or_b32_e32 v90, 0x200, v4
	v_lshlrev_b32_e32 v4, 4, v3
	v_mov_b32_e32 v5, v61
	s_load_dwordx4 s[64:67], s[94:95], 0x58
	s_load_dwordx2 s[34:35], s[94:95], 0x70
	s_add_i32 s11, s8, 0
	v_lshlrev_b32_e32 v2, 3, v0
	v_lshl_add_u64 v[6:7], s[20:21], 0, v[4:5]
	s_mov_b64 s[8:9], 0x3a00000
	v_and_b32_e32 v2, 0x78, v2
	v_lshl_add_u64 v[66:67], v[6:7], 0, s[8:9]
	v_or_b32_e32 v5, s10, v1
	v_lshlrev_b32_e32 v166, 1, v5
	v_and_b32_e32 v166, 0xf0, v166
	s_movk_i32 s8, 0x110
	v_lshl_or_b32 v3, v3, 2, s14
	v_ashrrev_i32_e32 v91, 4, v0
	v_add_u32_e32 v9, 0x200, v0
	v_add_u32_e32 v10, 0x400, v0
	v_add_u32_e32 v0, 0x600, v0
	v_lshlrev_b32_e32 v60, 2, v2
	v_mul_lo_u32 v5, v5, s8
	v_ashrrev_i32_e32 v92, 4, v9
	v_ashrrev_i32_e32 v93, 4, v10
	v_ashrrev_i32_e32 v94, 4, v0
	s_movk_i32 s8, 0x210
	v_mul_u32_u24_e32 v3, 0x210, v3
	v_lshlrev_b32_e32 v1, 2, v1
	v_add_u32_e32 v5, 0, v5
	v_add_u32_e32 v6, 0, v60
	v_lshl_add_u32 v7, v91, 1, 0
	v_mul_u32_u24_e32 v8, 0x110, v2
	v_lshl_add_u32 v9, v92, 1, 0
	v_lshl_add_u32 v10, v93, 1, 0
	v_lshl_add_u32 v0, v94, 1, 0
	v_add3_u32 v95, s11, v3, v1
	v_mul_lo_u32 v1, v91, s8
	v_mul_lo_u32 v3, v92, s8
	v_mul_lo_u32 v11, v93, s8
	v_mul_lo_u32 v12, v94, s8
	v_lshlrev_b32_e32 v70, 1, v2
	s_mov_b32 s63, 0
	s_waitcnt lgkmcnt(0)
	v_lshl_add_u64 v[62:63], s[64:65], 0, v[60:61]
	v_lshl_add_u64 v[64:65], s[66:67], 0, v[60:61]
	s_lshl_b32 s27, s2, 7
	s_lshl_b32 s37, s31, 7
	s_lshl_b32 s42, s2, 5
	s_mov_b32 s43, 0x3b000000
	s_movk_i32 s44, 0x2400
	v_mov_b64_e32 v[68:69], s[46:47]
	v_mov_b32_e32 v72, v70
	v_mov_b32_e32 v73, v61
	s_movk_i32 s45, 0x1000
	v_xor_b32_e32 v7, v7, v70
	v_xor_b32_e32 v9, v9, v70
	v_xor_b32_e32 v10, v10, v70
	v_xor_b32_e32 v0, v0, v70
	v_add_u32_e32 v96, v7, v8
	v_add_u32_e32 v97, v9, v8
	v_add_u32_e32 v98, v10, v8
	v_add_u32_e32 v99, v0, v8
	s_movk_i32 s64, 0x2000
	v_add_u32_e32 v100, v6, v1
	v_add_u32_e32 v101, v6, v3
	v_add_u32_e32 v102, v6, v11
	v_add_u32_e32 v103, v6, v12
	v_add_u32_e32 v104, v5, v4
	v_xor_b32_e32 v167, v4, v166
	v_mov_b32_e32 v168, v167
	v_add_u32_e32 v150, v5, v168
	v_xor_b32_e32 v169, 64, v168
	v_add_u32_e32 v169, v5, v169
	v_add_u32_e32 v158, 0x2200, v169
	v_xor_b32_e32 v168, 0x20, v167
	v_add_u32_e32 v151, v5, v168
	v_xor_b32_e32 v169, 64, v168
	v_add_u32_e32 v169, v5, v169
	v_add_u32_e32 v159, 0x2200, v169
	v_xor_b32_e32 v168, 0x40, v167
	v_add_u32_e32 v152, v5, v168
	v_xor_b32_e32 v169, 64, v168
	v_add_u32_e32 v169, v5, v169
	v_add_u32_e32 v160, 0x2200, v169
	v_xor_b32_e32 v168, 0x60, v167
	v_add_u32_e32 v153, v5, v168
	v_xor_b32_e32 v169, 64, v168
	v_add_u32_e32 v169, v5, v169
	v_add_u32_e32 v161, 0x2200, v169
	v_xor_b32_e32 v168, 0x80, v167
	v_add_u32_e32 v154, v5, v168
	v_xor_b32_e32 v169, 64, v168
	v_add_u32_e32 v169, v5, v169
	v_add_u32_e32 v162, 0x2200, v169
	v_xor_b32_e32 v168, 0xa0, v167
	v_add_u32_e32 v155, v5, v168
	v_xor_b32_e32 v169, 64, v168
	v_add_u32_e32 v169, v5, v169
	v_add_u32_e32 v163, 0x2200, v169
	v_xor_b32_e32 v168, 0xc0, v167
	v_add_u32_e32 v156, v5, v168
	v_xor_b32_e32 v169, 64, v168
	v_add_u32_e32 v169, v5, v169
	v_add_u32_e32 v164, 0x2200, v169
	v_xor_b32_e32 v168, 0xe0, v167
	v_add_u32_e32 v157, v5, v168
	v_xor_b32_e32 v169, 64, v168
	v_add_u32_e32 v169, v5, v169
	v_add_u32_e32 v165, 0x2200, v169
	s_mov_b32 s65, s2
	s_branch .LBB0_958

; #define LAS __attribute__((address_space(3)))
; __device__ __forceinline__ void phase_sgu(const Params& p, int l, LAS unsigned char* lds, const bf16_t* proj, const float* sgst, const bf16_t* sgw, bf16_t* ymix, int G, int wv) {
;     ...
; #pragma unroll
;         for (int ks = 0; ks < 8; ++ks) if (ks < 2 * tb + 2) {
;             const bf16x8 b0 = *(const LAS bf16x8*)(tb0 + ks * 32), b1 = *(const LAS bf16x8*)(tb0 + 32 * SG_ROW + ks * 32);
;             acc0 = __builtin_amdgcn_mfma_f32_32x32x16_bf16(af[ks], b0, acc0, 0, 0, 0);
;             acc1 = __builtin_amdgcn_mfma_f32_32x32x16_bf16(af[ks], b1, acc1, 0, 0, 0);
;         }
.LBB0_979:
	ds_read_b128 v[32:35], v154
	ds_read_b128 v[36:39], v162
	s_waitcnt lgkmcnt(1)
	v_mfma_f32_32x32x16_bf16 v[0:15], v[44:47], v[32:35], v[0:15]
	s_waitcnt lgkmcnt(0)
	v_mfma_f32_32x32x16_bf16 v[16:31], v[44:47], v[36:39], v[16:31]
	s_and_b64 vcc, exec, s[14:15]
	s_cbranch_vccnz .LBB0_977
.LBB0_980:
	ds_read_b128 v[32:35], v155
	ds_read_b128 v[36:39], v163
	s_waitcnt lgkmcnt(1)
	v_mfma_f32_32x32x16_bf16 v[0:15], v[48:51], v[32:35], v[0:15]
	s_waitcnt lgkmcnt(0)
	v_mfma_f32_32x32x16_bf16 v[16:31], v[48:51], v[36:39], v[16:31]
	s_and_b64 vcc, exec, s[16:17]
	s_cbranch_vccnz .LBB0_978
.LBB0_981:
	ds_read_b128 v[32:35], v156
	ds_read_b128 v[36:39], v164
	s_waitcnt lgkmcnt(1)
	v_mfma_f32_32x32x16_bf16 v[0:15], v[52:55], v[32:35], v[0:15]
	s_waitcnt lgkmcnt(0)
	v_mfma_f32_32x32x16_bf16 v[16:31], v[52:55], v[36:39], v[16:31]
	s_and_b64 vcc, exec, s[16:17]
	s_cbranch_vccnz .LBB0_957
